# GEMM phase prologues: K-tile 1 stage loads issued before the first wait/barrier (wait counts adjusted), 5 instances
# speedup vs baseline: 1.0069x; 1.0015x over previous
.LBB0_441:
	v_bfe_u32 v17, v166, 4, 2
	v_and_b32_e32 v16, 15, v166
	v_lshlrev_b32_e32 v18, 4, v17
	v_lshl_or_b32 v136, s10, 6, v16
	v_lshl_or_b32 v16, v16, 6, v18
	v_lshlrev_b32_e32 v18, 2, v166
	s_sext_i32_i8 s7, s8
	s_lshl_b32 s8, s10, 13
	v_and_b32_e32 v18, 32, v18
	v_bitop3_b32 v19, v16, s8, v18 bitop3:0xde
	s_lshl_b32 s8, s11, 5
	s_and_b32 s12, s8, 0x60
	s_add_i32 m0, s67, 0x18000
	v_lshl_add_u64 v[8:9], v[8:9], 0, s[22:23]
	s_lshl_b32 s8, s12, 7
	global_load_lds_dwordx4 v[8:9], off
	v_lshl_add_u64 v[6:7], v[6:7], 0, s[22:23]
	s_add_i32 m0, s67, 0x1a000
	s_add_i32 s80, s67, 0x8000
	s_add_i32 s81, s67, 0xa000
	global_load_lds_dwordx4 v[6:7], off
	v_lshl_add_u64 v[2:3], v[2:3], 0, s[22:23]
	s_mov_b32 m0, s80
	s_add_u32 s10, s28, 0x40080
	global_load_lds_dwordx4 v[2:3], off
	v_lshl_add_u64 v[2:3], v[4:5], 0, s[22:23]
	s_mov_b32 m0, s81
	s_addc_u32 s11, s29, 0
	global_load_lds_dwordx4 v[2:3], off
	s_add_i32 m0, s67, 0x1c000
	v_lshl_add_u64 v[2:3], s[10:11], 0, v[0:1]
	global_load_lds_dwordx4 v[2:3], off
	v_lshl_add_u64 v[2:3], s[10:11], 0, v[130:131]
	s_add_i32 m0, s67, 0x1e000
	s_cmpk_lt_u32 s9, 0x100
	global_load_lds_dwordx4 v[2:3], off
	s_waitcnt vmcnt(8)
	s_barrier
	v_lshlrev_b32_e32 v2, 14, v13
	v_and_b32_e32 v2, 0xffff8000, v2
	v_lshl_add_u32 v2, v14, 11, v2
	v_and_b32_e32 v3, 1, v13
	v_lshl_or_b32 v2, v3, 6, v2
	v_lshl_add_u32 v132, v15, 1, v2
	v_lshlrev_b32_e32 v2, 14, v10
	v_and_b32_e32 v2, 0xffff8000, v2
	s_waitcnt vmcnt(6)
	v_lshl_add_u32 v2, v11, 11, v2
	v_and_b32_e32 v3, 1, v10
	v_lshl_or_b32 v2, v3, 6, v2
	v_bitop3_b32 v137, s8, v16, v18 bitop3:0xf6
	s_cselect_b64 s[8:9], -1, 0
	s_ashr_i32 s82, s63, 31
	v_lshl_or_b32 v138, v17, 2, s12
	v_mov_b32_e32 v133, v1
	v_lshl_add_u32 v134, v12, 1, v2
	v_mov_b32_e32 v135, v1
	s_mov_b32 s83, 0
	v_add_u32_e32 v139, 0, v19
	s_barrier
	s_branch .LBB0_444

.LBB0_586:
	s_add_u32 s6, s58, 0x28100000
	s_addc_u32 s7, s59, 0
	v_and_b32_e32 v167, 15, v166
	s_lshl_b32 s1, s2, 6
	v_lshrrev_b32_e32 v15, 1, v166
	v_writelane_b32 v254, s6, 42
	v_or_b32_e32 v188, s1, v167
	v_and_b32_e32 v15, 24, v15
	v_writelane_b32 v254, s7, 43
	v_lshlrev_b32_e32 v16, 1, v15
	v_lshlrev_b32_e32 v17, 2, v188
	v_writelane_b32 v254, s1, 41
	v_lshl_or_b32 v16, v167, 6, v16
	s_lshl_b32 s1, s2, 13
	v_and_b32_e32 v18, 32, v17
	v_bitop3_b32 v18, v16, s1, v18 bitop3:0xde
	s_lshl_b32 s1, s3, 5
	s_and_b32 s1, s1, 0x60
	s_lshl_b32 s2, s1, 7
	s_add_u32 s16, s58, s8
	v_lshlrev_b32_e32 v19, 2, v166
	s_addc_u32 s17, s59, s9
	s_add_i32 m0, s67, 0x18000
	v_lshl_add_u64 v[6:7], v[6:7], 0, s[22:23]
	v_and_b32_e32 v19, 32, v19
	global_load_lds_dwordx4 v[6:7], off
	v_lshl_add_u64 v[4:5], v[4:5], 0, s[22:23]
	s_add_i32 m0, s67, 0x1a000
	s_add_i32 s6, s67, 0x8000
	s_add_i32 s7, s67, 0xa000
	v_bitop3_b32 v189, s2, v16, v19 bitop3:0xf6
	global_load_lds_dwordx4 v[4:5], off
	v_lshl_add_u64 v[2:3], v[2:3], 0, s[22:23]
	s_mov_b32 m0, s6
	s_add_u32 s2, s4, 0x40080
	global_load_lds_dwordx4 v[2:3], off
	v_lshl_add_u64 v[2:3], v[8:9], 0, s[22:23]
	s_mov_b32 m0, s7
	s_addc_u32 s3, s5, 0
	global_load_lds_dwordx4 v[2:3], off
	s_add_i32 m0, s67, 0x1c000
	v_lshl_add_u64 v[2:3], s[2:3], 0, v[132:133]
	global_load_lds_dwordx4 v[2:3], off
	v_lshl_add_u64 v[2:3], s[2:3], 0, v[136:137]
	s_add_i32 m0, s67, 0x1e000
	s_cmpk_lt_u32 s18, 0x100
	global_load_lds_dwordx4 v[2:3], off
	s_waitcnt vmcnt(8)
	s_barrier
	v_lshlrev_b32_e32 v2, 14, v12
	v_and_b32_e32 v2, 0xffff8000, v2
	v_lshl_add_u32 v2, v13, 11, v2
	v_and_b32_e32 v3, 1, v12
	v_lshl_or_b32 v2, v3, 6, v2
	s_cselect_b64 s[2:3], -1, 0
	v_lshl_add_u32 v138, v14, 1, v2
	v_lshlrev_b32_e32 v2, 14, v0
	v_writelane_b32 v254, s2, 44
	v_subrev_co_u32_e32 v191, vcc, 13, v167
	v_and_b32_e32 v2, 0xffff8000, v2
	s_waitcnt vmcnt(6)
	v_writelane_b32 v254, s3, 45
	s_or_b64 s[2:3], s[38:39], vcc
	v_lshl_add_u32 v2, v10, 11, v2
	v_and_b32_e32 v0, 1, v0
	v_or_b32_e32 v190, s1, v15
	v_writelane_b32 v254, s2, 46
	s_add_i32 s1, 0, 0x20000
	v_lshl_or_b32 v0, v0, 6, v2
	v_writelane_b32 v254, s3, 47
	v_add_u32_e32 v192, s1, v17
	v_mov_b32_e32 v139, v1
	v_lshl_add_u32 v140, v11, 1, v0
	v_mov_b32_e32 v141, v1
	s_mov_b32 s19, 0
	v_add_u32_e32 v193, 0, v18
	s_mov_b32 s18, 0
	s_barrier
	s_branch .LBB0_589

.LBB0_885:
	v_readlane_b32 s2, v254, 11
	v_readlane_b32 s3, v254, 12
	s_cmp_eq_u32 s2, 0
	s_cselect_b32 s9, s41, s15
	s_cselect_b32 s8, s40, s14
	s_lshl_b64 s[2:3], s[94:95], 21
	s_add_u32 s2, s58, s2
	v_bfe_u32 v19, v166, 4, 2
	s_addc_u32 s3, s59, s3
	v_and_b32_e32 v18, 15, v166
	v_lshlrev_b32_e32 v21, 4, v19
	s_add_u32 s10, s2, 0x28c00000
	v_lshl_or_b32 v144, s1, 6, v18
	v_lshl_or_b32 v18, v18, 6, v21
	v_lshlrev_b32_e32 v21, 2, v166
	s_addc_u32 s11, s3, 0
	s_and_b32 s57, s0, 3
	s_lshl_b32 s0, s1, 13
	v_and_b32_e32 v21, 32, v21
	s_add_i32 m0, s31, 0x18000
	v_lshl_add_u64 v[8:9], v[8:9], 0, s[22:23]
	v_bitop3_b32 v22, v18, s0, v21 bitop3:0xde
	s_lshl_b32 s0, s57, 12
	global_load_lds_dwordx4 v[8:9], off
	v_lshl_add_u64 v[6:7], v[6:7], 0, s[22:23]
	s_add_i32 m0, s31, 0x1a000
	s_add_i32 s61, s31, 0x8000
	s_add_i32 s64, s31, 0xa000
	v_bitop3_b32 v145, s0, v18, v21 bitop3:0xf6
	global_load_lds_dwordx4 v[6:7], off
	v_lshl_add_u64 v[2:3], v[2:3], 0, s[22:23]
	s_mov_b32 m0, s61
	s_add_u32 s0, s24, 0xb0080
	global_load_lds_dwordx4 v[2:3], off
	v_lshl_add_u64 v[2:3], v[4:5], 0, s[22:23]
	s_mov_b32 m0, s64
	s_addc_u32 s1, s25, 0
	global_load_lds_dwordx4 v[2:3], off
	s_add_i32 m0, s31, 0x1c000
	v_lshl_add_u64 v[2:3], s[0:1], 0, v[0:1]
	global_load_lds_dwordx4 v[2:3], off
	v_lshl_add_u64 v[2:3], s[0:1], 0, v[134:135]
	s_add_i32 m0, s31, 0x1e000
	s_movk_i32 s5, 0xb00
	global_load_lds_dwordx4 v[2:3], off
	s_waitcnt vmcnt(8)
	s_barrier
	s_cmpk_lt_u32 s4, 0x100
	v_lshrrev_b32_e32 v3, 1, v14
	v_mul_lo_u32 v2, v16, s5
	s_mov_b32 s4, 0xb000
	v_mad_u64_u32 v[2:3], s[0:1], v3, s4, v[2:3]
	v_or_b32_e32 v2, v2, v15
	v_add_lshl_u32 v2, v2, v17, 1
	v_mov_b32_e32 v3, v1
	s_mov_b64 s[16:17], 0xb0080
	v_lshl_add_u64 v[136:137], v[2:3], 0, s[16:17]
	v_lshrrev_b32_e32 v3, 1, v10
	v_mul_lo_u32 v2, v12, s5
	v_mad_u64_u32 v[2:3], s[0:1], v3, s4, v[2:3]
	s_waitcnt vmcnt(6)
	v_or_b32_e32 v2, v2, v11
	v_lshlrev_b32_e32 v20, 3, v19
	v_add_lshl_u32 v2, v2, v13, 1
	v_mov_b32_e32 v3, v1
	s_mov_b32 s39, 0
	v_lshl_or_b32 v146, s57, 5, v20
	s_cselect_b64 s[12:13], -1, 0
	v_cmp_eq_u32_e64 s[2:3], 0, v19
	s_ashr_i32 s65, s63, 31
	s_ashr_i32 s66, s80, 31
	v_lshl_add_u64 v[138:139], v[2:3], 0, s[16:17]
	v_add_u32_e32 v147, 0, v22
	s_barrier
	s_branch .LBB0_889

.LBB0_954:
	s_lshl_b32 s5, s5, 5
	s_and_b32 s11, s5, 0x60
	s_add_i32 m0, s34, 0x18000
	v_lshl_add_u64 v[8:9], v[8:9], 0, s[22:23]
	s_lshl_b32 s10, s4, 13
	s_lshl_b32 s5, s11, 7
	global_load_lds_dwordx4 v[8:9], off
	v_lshl_add_u64 v[6:7], v[6:7], 0, s[22:23]
	s_add_i32 m0, s34, 0x1a000
	s_add_i32 s57, s34, 0x8000
	s_add_i32 s61, s34, 0xa000
	global_load_lds_dwordx4 v[6:7], off
	v_lshl_add_u64 v[2:3], v[2:3], 0, s[22:23]
	s_mov_b32 m0, s57
	s_add_u32 s6, s20, 0x40080
	global_load_lds_dwordx4 v[2:3], off
	v_lshl_add_u64 v[2:3], v[4:5], 0, s[22:23]
	s_mov_b32 m0, s61
	s_addc_u32 s7, s21, 0
	global_load_lds_dwordx4 v[2:3], off
	s_add_i32 m0, s34, 0x1c000
	v_lshl_add_u64 v[2:3], s[6:7], 0, v[0:1]
	global_load_lds_dwordx4 v[2:3], off
	v_lshl_add_u64 v[2:3], s[6:7], 0, v[130:131]
	s_add_i32 m0, s34, 0x1e000
	v_lshlrev_b32_e32 v6, 2, v166
	global_load_lds_dwordx4 v[2:3], off
	s_waitcnt vmcnt(8)
	s_barrier
	v_lshrrev_b32_e32 v3, 1, v166
	v_and_b32_e32 v2, 15, v166
	v_and_b32_e32 v3, 24, v3
	v_lshl_or_b32 v142, s4, 6, v2
	v_lshlrev_b32_e32 v4, 1, v3
	v_lshl_or_b32 v2, v2, 6, v4
	v_lshlrev_b32_e32 v4, 2, v142
	v_and_b32_e32 v5, 32, v4
	v_and_b32_e32 v6, 32, v6
	v_bitop3_b32 v5, v2, s10, v5 bitop3:0xde
	v_bitop3_b32 v143, s5, v2, v6 bitop3:0xf6
	v_lshlrev_b32_e32 v2, 14, v10
	v_and_b32_e32 v2, 0xffff8000, v2
	v_or_b32_e32 v144, s11, v3
	v_lshl_add_u32 v2, v11, 11, v2
	v_and_b32_e32 v3, 1, v10
	v_lshl_or_b32 v2, v3, 6, v2
	v_lshl_add_u32 v136, v12, 1, v2
	v_lshlrev_b32_e32 v2, 14, v14
	v_and_b32_e32 v2, 0xffff8000, v2
	s_waitcnt vmcnt(6)
	s_cmpk_lt_u32 s3, 0x100
	v_lshl_add_u32 v2, v13, 11, v2
	v_and_b32_e32 v3, 1, v14
	s_sext_i32_i16 s9, s2
	s_cselect_b64 s[4:5], -1, 0
	s_add_i32 s2, 0, 0x20000
	v_lshl_or_b32 v2, v3, 6, v2
	v_add_u32_e32 v145, s2, v4
	v_mov_b32_e32 v137, v1
	v_lshl_add_u32 v138, v15, 1, v2
	v_mov_b32_e32 v139, v1
	s_mov_b32 s66, 0
	v_add_u32_e32 v146, 0, v5
	s_mov_b32 s64, 0
	s_barrier
	s_branch .LBB0_957

.LBB0_983:
	s_add_u32 s8, s58, 0x1b800000
	s_addc_u32 s9, s59, 0
	s_lshl_b32 s4, s16, 22
	s_bitset1_b32 s4, 21
	s_add_u32 s4, s58, s4
	v_bfe_u32 v17, v166, 4, 2
	s_addc_u32 s5, s59, 0
	v_and_b32_e32 v16, 15, v166
	v_lshlrev_b32_e32 v19, 4, v17
	s_add_u32 s10, s4, 0x28c00000
	v_lshl_or_b32 v144, s3, 6, v16
	v_lshl_or_b32 v16, v16, 6, v19
	v_lshlrev_b32_e32 v19, 2, v166
	s_addc_u32 s11, s5, 0
	s_and_b32 s65, s2, 3
	s_lshl_b32 s2, s3, 13
	v_and_b32_e32 v19, 32, v19
	s_add_i32 m0, s35, 0x18000
	v_lshl_add_u64 v[8:9], v[8:9], 0, s[22:23]
	v_bitop3_b32 v20, v16, s2, v19 bitop3:0xde
	s_lshl_b32 s2, s65, 12
	global_load_lds_dwordx4 v[8:9], off
	v_lshl_add_u64 v[6:7], v[6:7], 0, s[22:23]
	s_add_i32 m0, s35, 0x1a000
	s_add_i32 s66, s35, 0x8000
	s_add_i32 s67, s35, 0xa000
	v_bitop3_b32 v145, s2, v16, v19 bitop3:0xf6
	global_load_lds_dwordx4 v[6:7], off
	v_lshl_add_u64 v[2:3], v[2:3], 0, s[22:23]
	s_mov_b32 m0, s66
	s_add_u32 s2, s26, 0x40080
	global_load_lds_dwordx4 v[2:3], off
	v_lshl_add_u64 v[2:3], v[4:5], 0, s[22:23]
	s_mov_b32 m0, s67
	s_addc_u32 s3, s27, 0
	global_load_lds_dwordx4 v[2:3], off
	s_add_i32 m0, s35, 0x1c000
	v_lshl_add_u64 v[2:3], s[2:3], 0, v[0:1]
	global_load_lds_dwordx4 v[2:3], off
	v_lshl_add_u64 v[2:3], s[2:3], 0, v[134:135]
	s_add_i32 m0, s35, 0x1e000
	v_lshlrev_b32_e32 v18, 3, v17
	global_load_lds_dwordx4 v[2:3], off
	s_waitcnt vmcnt(8)
	s_barrier
	v_lshlrev_b32_e32 v2, 14, v13
	v_and_b32_e32 v2, 0xffff8000, v2
	v_lshl_add_u32 v2, v14, 11, v2
	v_and_b32_e32 v3, 1, v13
	v_lshl_or_b32 v2, v3, 6, v2
	v_lshl_add_u32 v136, v15, 1, v2
	v_lshlrev_b32_e32 v2, 14, v10
	v_and_b32_e32 v2, 0xffff8000, v2
	s_waitcnt vmcnt(6)
	v_lshl_add_u32 v2, v11, 11, v2
	v_and_b32_e32 v3, 1, v10
	s_cmpk_lt_u32 s12, 0x100
	v_lshl_or_b32 v2, v3, 6, v2
	v_lshl_or_b32 v146, s65, 5, v18
	s_cselect_b64 s[12:13], -1, 0
	s_mov_b32 s68, 0
	v_cmp_eq_u32_e64 s[2:3], 0, v17
	s_ashr_i32 s69, s63, 31
	s_ashr_i32 s70, s80, 31
	v_mov_b32_e32 v137, v1
	v_lshl_add_u32 v138, v12, 1, v2
	v_mov_b32_e32 v139, v1
	v_add_u32_e32 v147, 0, v20
	s_barrier
	s_branch .LBB0_986
